# phase-2 conv edge loop: conv weights/bias fetched as 8 dwordx4 preloads instead of 12 serialized dwordx2 loads with drains
# speedup vs baseline: 1.1025x; 1.0029x over previous
; __device__ __forceinline__ unsigned cvt_pk_bf16(float lo, float hi) { unsigned r; asm volatile("v_cvt_pk_bf16_f32 %0, %1, %2" : "=v"(r) : "v"(lo), "v"(hi)); return r; }
; __device__ __forceinline__ float bf_lo(unsigned w) { return __uint_as_float(w << 16); }
; __device__ __forceinline__ float bf_hi(unsigned w) { return __uint_as_float(w & 0xffff0000u); }
; __device__ __forceinline__ float sigmoidf_(float x) { return 1.0f / (1.0f + __expf(-x)); }
; __device__ void phase_conv(const Params& P, const int G, const int bid) {
;     ...
;     for (int it = bid * 512 + tid; it < 512 * 2 * 128; it += G * 512) { const int ch = it & 127, which = (it >> 7) & 1, g = it >> 8; const int col = ch * 8;
;         const int gs = g < 256 ? (g & 127) : ((g - 256) & 31), ng = g < 256 ? 128 : 32; const bool seq_first = gs == 0, seq_last = gs == ng - 1;
;         const bf16_t* pp = which ? HQ + (size_t)(g * 4 + 2) * 1024 : HQ + (size_t)((seq_first ? g : g - 1) * 4 + 3) * 1024;
;         const bf16_t* pc = HQ + (size_t)(g * 4 + (which ? 3 : 0)) * 1024;
;         const bf16_t* pn = which ? HQ + (size_t)((seq_last ? g : g + 1) * 4 + 0) * 1024 : HQ + (size_t)(g * 4 + 1) * 1024;
;         const float mp = (!which && seq_first) ? 0.f : 1.f, mn = (which && seq_last) ? 0.f : 1.f, mul = col < 512 ? 0.08838834764831845f : 1.0f;
;         const u32x4 gp = *(const u32x4*)(pp + col), gc = *(const u32x4*)(pc + col), gn = *(const u32x4*)(pn + col); u32x4 ov;
; #pragma unroll
;         for (int q = 0; q < 4; ++q) { const int c = col + 2 * q;
;             const float u0 = bf_lo(gp[q]) * mp * cw[c] + bf_lo(gc[q]) * cw[1024 + c] + bf_lo(gn[q]) * mn * cw[2048 + c] + cbv[c];
;             const float u1 = bf_hi(gp[q]) * mp * cw[c + 1] + bf_hi(gc[q]) * cw[1024 + c + 1] + bf_hi(gn[q]) * mn * cw[2048 + c + 1] + cbv[c + 1];
;             ov[q] = cvt_pk_bf16(u0 * sigmoidf_(u0) * mul, u1 * sigmoidf_(u1) * mul); }
.LBB0_578:
	s_or_b64 exec, exec, s[8:9]
	v_and_b32_e32 v14, 0x3f8, v21
	s_movk_i32 s11, 0x200
	s_and_b64 s[8:9], s[40:41], s[42:43]
	v_cmp_gt_u32_e64 s[40:41], s11, v14
	v_or_b32_e32 v8, v7, v5
	v_or_b32_e32 v0, v0, v6
	v_cndmask_b32_e64 v24, 1.0, v218, s[40:41]
	v_readlane_b32 s40, v254, 34
	v_ashrrev_i32_e32 v3, 31, v2
	v_ashrrev_i32_e32 v9, 31, v8
	v_ashrrev_i32_e32 v5, 31, v4
	v_cmp_eq_u32_e32 vcc, 0, v0
	v_lshlrev_b32_e32 v0, 1, v14
	v_lshlrev_b32_e32 v14, 2, v14
	v_mov_b32_e32 v15, v1
	v_readlane_b32 s52, v254, 46
	v_readlane_b32 s53, v254, 47
	v_lshlrev_b64 v[2:3], 11, v[2:3]
	v_lshlrev_b64 v[8:9], 11, v[8:9]
	v_lshlrev_b64 v[4:5], 11, v[4:5]
	v_readlane_b32 s41, v254, 35
	v_lshl_add_u64 v[16:17], s[52:53], 0, v[14:15]
	s_movk_i32 s11, 0x1000
	v_lshl_add_u64 v[2:3], s[4:5], 0, v[2:3]
	v_lshl_add_u64 v[8:9], s[4:5], 0, v[8:9]
	v_lshl_add_u64 v[10:11], s[4:5], 0, v[4:5]
	v_add_co_u32_e64 v18, s[40:41], s11, v16
	v_lshl_add_u64 v[2:3], v[2:3], 0, v[0:1]
	v_lshl_add_u64 v[6:7], v[8:9], 0, v[0:1]
	v_lshl_add_u64 v[10:11], v[10:11], 0, v[0:1]
	v_addc_co_u32_e64 v19, s[40:41], 0, v17, s[40:41]
	global_load_dwordx4 v[2:5], v[2:3], off
	v_add_co_u32_e64 v16, s[40:41], s83, v16
	global_load_dwordx4 v[6:9], v[6:7], off
	s_nop 0
	v_addc_co_u32_e64 v17, s[40:41], 0, v17, s[40:41]
	global_load_dwordx4 v[10:13], v[10:11], off
	v_readlane_b32 s54, v254, 48
	global_load_dwordx2 v[26:27], v14, s[52:53]
	v_readlane_b32 s55, v254, 49
	global_load_dwordx2 v[28:29], v[16:17], off offset:-4096
	global_load_dwordx2 v[30:31], v[16:17], off
	s_nop 2
	global_load_dwordx2 v[32:33], v14, s[54:55]
	global_load_dwordx4 v[44:47], v14, s[52:53]
	global_load_dwordx4 v[48:51], v14, s[52:53] offset:16
	global_load_dwordx4 v[52:55], v[18:19], off
	global_load_dwordx4 v[56:59], v[18:19], off offset:16
	global_load_dwordx4 v[60:63], v[16:17], off
	global_load_dwordx4 v[64:67], v[16:17], off offset:16
	global_load_dwordx4 v[68:71], v14, s[54:55]
	global_load_dwordx4 v[72:75], v14, s[54:55] offset:16
	v_add_u32_e32 v20, s0, v20
	v_add_u32_e32 v21, s10, v21
	v_readlane_b32 s42, v254, 36
	v_readlane_b32 s43, v254, 37
	v_readlane_b32 s44, v254, 38
	v_readlane_b32 s45, v254, 39
	v_readlane_b32 s46, v254, 40
	v_readlane_b32 s47, v254, 41
	v_readlane_b32 s48, v254, 42
	v_readlane_b32 s49, v254, 43
	v_readlane_b32 s50, v254, 44
	v_readlane_b32 s51, v254, 45
	s_waitcnt vmcnt(0)
	v_lshlrev_b32_e32 v34, 16, v2
	s_waitcnt vmcnt(5)
	v_lshlrev_b32_e32 v38, 16, v6
	v_and_b32_e32 v39, 0xffff0000, v6
	v_lshlrev_b32_e32 v40, 16, v7
	v_and_b32_e32 v41, 0xffff0000, v7
	v_cndmask_b32_e64 v7, 1.0, 0, s[8:9]
	v_cndmask_b32_e64 v6, 1.0, 0, vcc
	s_waitcnt vmcnt(4)
	v_lshlrev_b32_e32 v35, 16, v10
	v_pk_mul_f32 v[34:35], v[6:7], v[34:35]
	s_waitcnt vmcnt(3)
	v_mov_b32_e32 v36, v26
	s_waitcnt vmcnt(1)
	v_mov_b32_e32 v37, v30
	v_pk_mul_f32 v[34:35], v[36:37], v[34:35]
	v_mov_b32_e32 v30, v27
	v_fma_f32 v26, v28, v38, v34
	v_add_f32_e32 v26, v26, v35
	s_waitcnt vmcnt(0)
	v_add_f32_e32 v28, v32, v26
	v_and_b32_e32 v35, 0xffff0000, v10
	v_mul_f32_e32 v10, 0xbfb8aa3b, v28
	v_exp_f32_e32 v10, v10
	v_and_b32_e32 v34, 0xffff0000, v2
	v_pk_mul_f32 v[34:35], v[6:7], v[34:35]
	v_lshlrev_b32_e32 v32, 16, v3
	v_pk_mul_f32 v[26:27], v[34:35], v[30:31]
	v_add_f32_e32 v10, 1.0, v10
	v_fma_f32 v2, v29, v39, v26
	v_add_f32_e32 v2, v2, v27
	v_add_f32_e32 v2, v33, v2
	v_lshlrev_b32_e32 v33, 16, v11
	v_pk_mul_f32 v[32:33], v[6:7], v[32:33]
	v_rcp_f32_e32 v26, v10
	s_nop 0
	v_fma_f32 v30, -v10, v26, 1.0
	v_fma_f32 v10, v30, v26, v26
	v_mul_f32_e32 v26, 0xbfb8aa3b, v2
	v_exp_f32_e32 v26, v26
	v_mul_f32_e32 v10, v28, v10
	v_mul_f32_e32 v10, v24, v10
	v_and_b32_e32 v11, 0xffff0000, v11
	v_add_f32_e32 v26, 1.0, v26
	v_lshlrev_b32_e32 v25, 16, v8
	v_and_b32_e32 v15, 0xffff0000, v8
	v_lshlrev_b32_e32 v8, 16, v9
	v_rcp_f32_e32 v27, v26
	s_nop 0
	v_fma_f32 v30, -v26, v27, 1.0
	v_fma_f32 v26, v30, v27, v27
	v_mul_f32_e32 v2, v2, v26
	v_mul_f32_e32 v2, v24, v2
	v_cvt_pk_bf16_f32 v2, v10, v2
	v_mov_b64_e32 v[26:27], v[46:47]
	v_mov_b64_e32 v[28:29], v[54:55]
	v_mov_b64_e32 v[30:31], v[62:63]
	s_waitcnt vmcnt(2)
; __device__ __forceinline__ unsigned cvt_pk_bf16(float lo, float hi) { unsigned r; asm volatile("v_cvt_pk_bf16_f32 %0, %1, %2" : "=v"(r) : "v"(lo), "v"(hi)); return r; }
; __device__ __forceinline__ float bf_lo(unsigned w) { return __uint_as_float(w << 16); }
; __device__ __forceinline__ float bf_hi(unsigned w) { return __uint_as_float(w & 0xffff0000u); }
; __device__ __forceinline__ float sigmoidf_(float x) { return 1.0f / (1.0f + __expf(-x)); }
; __device__ void phase_conv(const Params& P, const int G, const int bid) {
;     ...
;         for (int q = 0; q < 4; ++q) { const int c = col + 2 * q;
;             const float u0 = bf_lo(gp[q]) * mp * cw[c] + bf_lo(gc[q]) * cw[1024 + c] + bf_lo(gn[q]) * mn * cw[2048 + c] + cbv[c];
;             const float u1 = bf_hi(gp[q]) * mp * cw[c + 1] + bf_hi(gc[q]) * cw[1024 + c + 1] + bf_hi(gn[q]) * mn * cw[2048 + c + 1] + cbv[c + 1];
;             ov[q] = cvt_pk_bf16(u0 * sigmoidf_(u0) * mul, u1 * sigmoidf_(u1) * mul); }
;         *(u32x4*)(proj + (size_t)(g * 64 + (which ? 63 : 0)) * NPROJ + 2048 + col) = ov; }
	v_mov_b32_e32 v34, v26
	s_waitcnt vmcnt(0)
	v_mov_b32_e32 v35, v30
	v_pk_mul_f32 v[32:33], v[32:33], v[34:35]
	v_mov_b32_e32 v30, v27
	v_fma_f32 v10, v28, v40, v32
	v_add_f32_e32 v10, v10, v33
	v_mov_b64_e32 v[32:33], v[70:71]
	s_waitcnt vmcnt(0)
	v_add_f32_e32 v26, v32, v10
	v_and_b32_e32 v10, 0xffff0000, v3
	v_pk_mul_f32 v[10:11], v[6:7], v[10:11]
	s_nop 0
	v_pk_mul_f32 v[10:11], v[10:11], v[30:31]
	v_lshlrev_b32_e32 v31, 16, v12
	v_fma_f32 v3, v29, v41, v10
	v_mul_f32_e32 v10, 0xbfb8aa3b, v26
	v_exp_f32_e32 v10, v10
	v_add_f32_e32 v3, v3, v11
	v_add_f32_e32 v3, v33, v3
	v_add_f32_e32 v10, 1.0, v10
	s_nop 0
	v_rcp_f32_e32 v11, v10
	s_nop 0
	v_fma_f32 v29, -v10, v11, 1.0
	v_fma_f32 v10, v29, v11, v11
	v_mul_f32_e32 v11, 0xbfb8aa3b, v3
	v_exp_f32_e32 v11, v11
	v_mul_f32_e32 v10, v26, v10
	v_mul_f32_e32 v10, v24, v10
	v_add_f32_e32 v11, 1.0, v11
	s_nop 0
	v_rcp_f32_e32 v26, v11
	s_nop 0
	v_fma_f32 v29, -v11, v26, 1.0
	v_fma_f32 v11, v29, v26, v26
	v_mul_f32_e32 v3, v3, v11
	v_mul_f32_e32 v3, v24, v3
	v_cvt_pk_bf16_f32 v3, v10, v3
	v_mov_b64_e32 v[10:11], v[48:49]
	v_mov_b64_e32 v[26:27], v[56:57]
	v_mov_b64_e32 v[28:29], v[64:65]
	v_lshlrev_b32_e32 v30, 16, v4
	v_pk_mul_f32 v[30:31], v[6:7], v[30:31]
	s_waitcnt vmcnt(2)
	v_mov_b32_e32 v32, v10
	s_waitcnt vmcnt(0)
	v_mov_b32_e32 v33, v28
	v_pk_mul_f32 v[30:31], v[30:31], v[32:33]
	v_and_b32_e32 v33, 0xffff0000, v12
	v_fma_f32 v10, v26, v25, v30
	v_add_f32_e32 v10, v10, v31
	v_mov_b64_e32 v[30:31], v[72:73]
	v_and_b32_e32 v32, 0xffff0000, v4
	v_pk_mul_f32 v[32:33], v[6:7], v[32:33]
	v_mov_b32_e32 v28, v11
	s_waitcnt vmcnt(0)
	v_add_f32_e32 v25, v30, v10
	v_pk_mul_f32 v[10:11], v[32:33], v[28:29]
	s_nop 0
	v_fma_f32 v4, v27, v15, v10
	v_mul_f32_e32 v10, 0xbfb8aa3b, v25
	v_exp_f32_e32 v10, v10
	v_add_f32_e32 v4, v4, v11
	v_add_f32_e32 v4, v31, v4
	v_add_f32_e32 v10, 1.0, v10
	s_nop 0
	v_rcp_f32_e32 v11, v10
	s_nop 0
	v_fma_f32 v26, -v10, v11, 1.0
	v_fma_f32 v10, v26, v11, v11
	v_mul_f32_e32 v11, 0xbfb8aa3b, v4
	v_exp_f32_e32 v11, v11
	v_mul_f32_e32 v10, v25, v10
	v_mul_f32_e32 v10, v24, v10
	v_add_f32_e32 v11, 1.0, v11
	s_nop 0
	v_rcp_f32_e32 v12, v11
	s_nop 0
	v_fma_f32 v26, -v11, v12, 1.0
	v_fma_f32 v11, v26, v12, v12
	v_mul_f32_e32 v4, v4, v11
	v_mul_f32_e32 v4, v24, v4
	v_cvt_pk_bf16_f32 v4, v10, v4
	v_mov_b64_e32 v[10:11], v[50:51]
	s_nop 0
	v_mov_b64_e32 v[18:19], v[58:59]
	v_lshlrev_b32_e32 v27, 16, v13
	v_mov_b64_e32 v[16:17], v[66:67]
	v_lshlrev_b32_e32 v26, 16, v5
	v_mov_b64_e32 v[14:15], v[74:75]
	v_pk_mul_f32 v[26:27], v[6:7], v[26:27]
	v_and_b32_e32 v12, 0xffff0000, v9
	v_and_b32_e32 v9, 0xffff0000, v13
	s_waitcnt vmcnt(3)
	v_mov_b32_e32 v28, v10
	s_waitcnt vmcnt(1)
	v_mov_b32_e32 v29, v16
	v_pk_mul_f32 v[26:27], v[26:27], v[28:29]
	v_mov_b32_e32 v16, v11
	v_fma_f32 v8, v18, v8, v26
	v_add_f32_e32 v8, v8, v27
	s_waitcnt vmcnt(0)
	v_add_f32_e32 v10, v14, v8
	v_and_b32_e32 v8, 0xffff0000, v5
	v_pk_mul_f32 v[6:7], v[6:7], v[8:9]
	s_nop 0
	v_pk_mul_f32 v[6:7], v[6:7], v[16:17]
	s_nop 0
	v_fma_f32 v5, v19, v12, v6
	v_mul_f32_e32 v6, 0xbfb8aa3b, v10
	v_exp_f32_e32 v6, v6
	v_add_f32_e32 v5, v5, v7
	v_add_f32_e32 v5, v15, v5
	v_add_f32_e32 v6, 1.0, v6
	s_nop 0
	v_rcp_f32_e32 v7, v6
	s_nop 0
	v_fma_f32 v11, -v6, v7, 1.0
	v_fma_f32 v6, v11, v7, v7
	v_mul_f32_e32 v7, 0xbfb8aa3b, v5
	v_exp_f32_e32 v7, v7
	v_mul_f32_e32 v6, v10, v6
	v_mul_f32_e32 v6, v24, v6
	v_add_f32_e32 v7, 1.0, v7
	s_mov_b32 s8, 0x1ffff
	v_rcp_f32_e32 v8, v7
	s_nop 0
	v_fma_f32 v11, -v7, v8, 1.0
	v_fma_f32 v7, v11, v8, v8
	v_mul_f32_e32 v5, v5, v7
	v_mul_f32_e32 v5, v24, v5
	v_cvt_pk_bf16_f32 v5, v6, v5
	v_lshl_or_b32 v6, v22, 6, v23
	v_ashrrev_i32_e32 v7, 31, v6
	v_lshlrev_b64 v[6:7], 13, v[6:7]
	v_lshl_add_u64 v[6:7], s[22:23], 0, v[6:7]
	v_lshl_add_u64 v[6:7], v[6:7], 0, v[0:1]
	v_add_co_u32_e32 v6, vcc, 0x1000, v6
	s_nop 1
	v_addc_co_u32_e32 v7, vcc, 0, v7, vcc
	v_cmp_lt_i32_e32 vcc, s8, v20
	s_or_b64 s[6:7], vcc, s[6:7]
	global_store_dwordx4 v[6:7], v[2:5], off
	s_andn2_b64 exec, exec, s[6:7]
	s_cbranch_execz .LBB0_587
